# grid barrier: waiting blocks poll the top-level generation word directly instead of the per-XCD relay word
# speedup vs baseline: 1.0128x; 1.0128x over previous
; __device__ __forceinline__ unsigned xb_ld(unsigned* p)              { return __hip_atomic_load(p, __ATOMIC_RELAXED, __HIP_MEMORY_SCOPE_AGENT); }
; __device__ __forceinline__ unsigned xb_add(unsigned* p, unsigned v) { return __hip_atomic_fetch_add(p, v, __ATOMIC_RELAXED, __HIP_MEMORY_SCOPE_AGENT); }
; #define XB_SPIN(cond, bar) do { unsigned _sp = 0; while (cond) { __builtin_amdgcn_s_sleep(1); \
;     if ((++_sp & 255u) == 0u) { if (xb_ld(&(bar)[XB_TMO])) break; if (_sp > XB_SPIN_CAP) { atomicAdd(&(bar)[XB_TMO], 1u); break; } } } } while (0)
; __device__ __forceinline__ void xcd_barrier(const XcdBarrier& b) {
;     ...
;         const unsigned old = xb_add(&bar[XB_XSUB(b.x)], 1u);
;         const unsigned gen = old / nloc;
;         if (old + 1u == (gen + 1u) * nloc) {
;             __builtin_amdgcn_fence(__ATOMIC_RELEASE, "agent");
;             asm volatile("s_waitcnt vmcnt(0)" ::: "memory");
;             const unsigned og = xb_add(&bar[XB_TOP], 1u);
;             const unsigned tg = og / nx;
;             if (og + 1u == (tg + 1u) * nx) xb_add(&bar[XB_TOPGEN], 1u);
;             else XB_SPIN(xb_ld(&bar[XB_TOPGEN]) == tg, bar);
;             __builtin_amdgcn_fence(__ATOMIC_ACQUIRE, "agent");
;             xb_add(&bar[XB_XGEN(b.x)], 1u);
;             asm volatile("s_waitcnt vmcnt(0)" ::: "memory");
;         } else {
;             XB_SPIN(xb_ld(&bar[XB_XGEN(b.x)]) == gen, bar);
.LBB0_820:
	v_readlane_b32 s4, v253, 2
	v_readlane_b32 s5, v253, 3
	v_cvt_f32_u32_e32 v1, v3
	v_sub_u32_e32 v5, 0, v3
	v_rcp_iflag_f32_e32 v1, v1
	s_nop 1
	global_atomic_add v4, v145, v194, s[4:5] sc0
	v_mul_f32_e32 v1, 0x4f7ffffe, v1
	v_cvt_u32_f32_e32 v1, v1
	v_mul_lo_u32 v5, v5, v1
	v_mul_hi_u32 v5, v1, v5
	v_add_u32_e32 v1, v1, v5
	s_waitcnt vmcnt(0)
	v_mul_hi_u32 v1, v4, v1
	v_mul_lo_u32 v5, v1, v3
	v_sub_u32_e32 v5, v4, v5
	v_add_u32_e32 v6, 1, v1
	v_cmp_ge_u32_e32 vcc, v5, v3
	v_add_u32_e32 v4, 1, v4
	s_nop 0
	v_cndmask_b32_e32 v1, v1, v6, vcc
	v_sub_u32_e32 v6, v5, v3
	v_cndmask_b32_e32 v5, v5, v6, vcc
	v_add_u32_e32 v6, 1, v1
	v_cmp_ge_u32_e32 vcc, v5, v3
	s_nop 1
	v_cndmask_b32_e32 v1, v1, v6, vcc
	v_mul_lo_u32 v5, v3, v1
	v_add_u32_e32 v3, v5, v3
	v_cmp_ne_u32_e32 vcc, v4, v3
	s_and_saveexec_b64 s[4:5], vcc
	s_xor_b64 s[4:5], exec, s[4:5]
	s_cbranch_execz .LBB0_834
	v_readlane_b32 s6, v253, 10
	v_readlane_b32 s7, v253, 11
	s_waitcnt lgkmcnt(0)
	s_nop 3
	global_load_dword v2, v145, s[6:7] sc1
	s_waitcnt vmcnt(0)
	v_cmp_eq_u32_e32 vcc, v2, v1
	s_and_saveexec_b64 s[6:7], vcc
	s_cbranch_execz .LBB0_833
	s_mov_b32 s18, 1
	s_mov_b64 s[8:9], 0
	s_branch .LBB0_824
